# P3->P4 and P5->P1 barriers: XCD releases itself after its L2 write-back and cross-XCD arrival; the wait for the other XCDs is deferred to the next phase's first tile epilogue (first store into the ali
# speedup vs baseline: 1.0130x; 1.0130x over previous
.LBB0_90:
	s_or_b64 exec, exec, s[6:7]
	s_lshl_b32 s3, s2, 3
	s_add_i32 s8, s80, s3
	s_cmpk_lt_i32 s2, 0x240
	s_cselect_b64 s[6:7], -1, 0
	v_writelane_b32 v253, s6, 5
	s_ashr_i32 s3, s2, 31
	s_ashr_i32 s83, s54, 31
	v_writelane_b32 v253, s7, 6
	s_lshr_b32 s6, s3, 29
	s_add_i32 s7, s2, s6
	s_ashr_i32 s6, s7, 3
	s_and_b32 s7, s7, -8
	s_sub_i32 s7, s2, s7
	s_cmpk_lt_i32 s54, 0x80
	s_cselect_b64 s[12:13], -1, 0
	v_writelane_b32 v253, s12, 7
	s_movk_i32 s87, 0x49
	v_mov_b32_e32 v1, 0
	v_writelane_b32 v253, s13, 8
	v_writelane_b32 v255, s84, 0
	v_readlane_b32 s12, v253, 1
	s_add_i32 s9, s12, 0x480
	s_cmpk_lt_i32 s12, 0x1280
	v_readlane_b32 s13, v253, 2
	v_writelane_b32 v253, s9, 9
	s_cselect_b64 s[14:15], -1, 0
	v_writelane_b32 v253, s14, 10
	s_cmpk_lt_i32 s12, 0x1700
	s_cselect_b64 s[12:13], -1, 0
	v_writelane_b32 v253, s15, 11
	v_writelane_b32 v253, s12, 12
	s_cmp_gt_i32 s2, 63
	v_writelane_b32 v255, s85, 1
	v_writelane_b32 v253, s13, 13
	s_cselect_b64 s[12:13], -1, 0
	v_writelane_b32 v253, s12, 14
	s_add_i32 s9, s8, 0xfffffe00
	s_addk_i32 s8, 0x280
	v_writelane_b32 v253, s13, 15
	s_cmpk_lt_i32 s9, 0x1280
	v_writelane_b32 v253, s8, 16
	s_cselect_b64 s[12:13], -1, 0
	v_writelane_b32 v253, s12, 17
	s_add_i32 s73, s85, 0xfffffe00
	s_cmpk_lt_i32 s9, 0x1700
	v_writelane_b32 v253, s13, 18
	v_writelane_b32 v253, s9, 19
	s_cselect_b64 s[8:9], -1, 0
	s_add_u32 s66, s0, 0x1200
	s_addc_u32 s67, s1, 0
	s_add_u32 s68, s0, 0x1400
	s_addc_u32 s69, s1, 0
	s_add_u32 s70, s0, 0x1500
	s_addc_u32 s71, s1, 0
	s_add_u32 s74, s0, 0x1600
	s_addc_u32 s75, s1, 0
	s_add_u32 s76, s0, 0x1700
	v_writelane_b32 v253, s8, 20
	s_addc_u32 s77, s1, 0
	v_writelane_b32 v255, s73, 2
	v_writelane_b32 v253, s9, 21
	s_add_u32 s8, s0, 0x1800
	s_addc_u32 s9, s1, 0
	v_writelane_b32 v253, s8, 22
	v_mov_b32_e32 v214, 0x358637bd
	v_mbcnt_hi_u32_b32 v252, -1, v76
	v_writelane_b32 v253, s9, 23
	s_add_u32 s8, s0, 0x1900
	s_addc_u32 s9, s1, 0
	v_writelane_b32 v253, s8, 24
	v_mov_b32_e32 v246, 0x1200
	v_mov_b64_e32 v[248:249], 0x100
	v_writelane_b32 v253, s9, 25
	s_add_u32 s8, s0, 0x1a00
	s_addc_u32 s9, s1, 0
	v_writelane_b32 v253, s8, 26
	s_movk_i32 s72, 0x2000
	s_mov_b32 s97, 0x1fffe0
	v_writelane_b32 v253, s9, 27
	s_add_u32 s8, s0, 0x1b00
	s_addc_u32 s9, s1, 0
	v_writelane_b32 v253, s8, 28
	s_mov_b32 s61, 0x10000
	s_mov_b32 s90, 0x800000
	v_writelane_b32 v253, s9, 29
	s_add_u32 s8, s0, 0x1c00
	s_addc_u32 s9, s1, 0
	v_writelane_b32 v253, s8, 30
	s_movk_i32 s91, 0x1200
	s_movk_i32 s33, 0x90
	v_writelane_b32 v253, s9, 31
	s_add_u32 s8, s0, 0x1d00
	s_addc_u32 s9, s1, 0
	v_writelane_b32 v253, s8, 32
	s_movk_i32 s92, 0x7fff
	s_movk_i32 s94, 0x1600
	v_writelane_b32 v253, s9, 33
	s_add_u32 s8, s0, 0x1e00
	s_addc_u32 s9, s1, 0
	v_writelane_b32 v253, s8, 34
	s_movk_i32 s95, 0x2400
	s_movk_i32 s96, 0x101
	v_writelane_b32 v253, s9, 35
	s_add_u32 s8, s0, 0x1f00
	s_addc_u32 s9, s1, 0
	v_writelane_b32 v253, s8, 36
	s_mov_b32 s52, 0
	s_mov_b64 s[88:89], 0
	v_writelane_b32 v253, s9, 37
	s_add_u32 s8, s0, 0x2000
	s_addc_u32 s9, s1, 0
	v_writelane_b32 v253, s8, 38
	s_mov_b64 s[14:15], -1
	s_mov_b64 s[28:29], 0x80
	v_writelane_b32 v253, s9, 39
	s_add_u32 s8, s0, 0x2100
	s_addc_u32 s9, s1, 0
	v_writelane_b32 v253, s8, 40
	s_mov_b64 s[34:35], 0x24000
	s_mov_b64 s[36:37], 0x48000
	v_writelane_b32 v253, s9, 41
	s_add_u32 s8, s0, 0x2200
	s_addc_u32 s9, s1, 0
	v_writelane_b32 v253, s8, 42
	s_nop 1
	v_writelane_b32 v253, s9, 43
	s_add_u32 s8, s0, 0x2300
	s_addc_u32 s9, s1, 0
	v_writelane_b32 v253, s8, 44
	s_cmp_eq_u32 s11, 15
	s_nop 0
	v_writelane_b32 v253, s9, 45
	s_cselect_b64 s[8:9], -1, 0
	v_writelane_b32 v253, s8, 46
	s_cmp_eq_u32 s11, 14
	s_nop 0
	v_writelane_b32 v253, s9, 47
	s_cselect_b64 s[8:9], -1, 0
	v_writelane_b32 v253, s8, 48
	s_cmp_eq_u32 s11, 13
	s_nop 0
	v_writelane_b32 v253, s9, 49
	s_cselect_b64 s[8:9], -1, 0
	v_writelane_b32 v253, s8, 50
	s_cmp_eq_u32 s11, 12
	s_nop 0
	v_writelane_b32 v253, s9, 51
	s_cselect_b64 s[8:9], -1, 0
	v_writelane_b32 v253, s8, 52
	s_cmp_eq_u32 s11, 11
	s_nop 0
	v_writelane_b32 v253, s9, 53
	s_cselect_b64 s[8:9], -1, 0
	v_writelane_b32 v253, s8, 54
	s_cmp_eq_u32 s11, 10
	s_nop 0
	v_writelane_b32 v253, s9, 55
	s_cselect_b64 s[8:9], -1, 0
	v_writelane_b32 v253, s8, 56
	s_cmp_eq_u32 s11, 9
	s_nop 0
	v_writelane_b32 v253, s9, 57
	s_cselect_b64 s[8:9], -1, 0
	v_writelane_b32 v253, s8, 58
	s_cmp_eq_u32 s11, 8
	s_nop 0
	v_writelane_b32 v253, s9, 59
	s_cselect_b64 s[8:9], -1, 0
	v_writelane_b32 v253, s8, 60
	s_cmp_eq_u32 s11, 7
	s_nop 0
	v_writelane_b32 v253, s9, 61
	s_cselect_b64 s[8:9], -1, 0
	v_writelane_b32 v253, s8, 62
	s_cmp_eq_u32 s11, 6
	s_nop 0
	v_writelane_b32 v253, s9, 63
	s_cselect_b64 s[8:9], -1, 0
	v_writelane_b32 v254, s8, 0
	s_cmp_eq_u32 s11, 5
	s_nop 0
	v_writelane_b32 v254, s9, 1
	s_cselect_b64 s[8:9], -1, 0
	v_writelane_b32 v254, s8, 2
	s_cmp_eq_u32 s11, 4
	s_nop 0
	v_writelane_b32 v254, s9, 3
	s_cselect_b64 s[8:9], -1, 0
	v_writelane_b32 v254, s8, 4
	s_cmp_eq_u32 s11, 3
	s_nop 0
	v_writelane_b32 v254, s9, 5
	s_cselect_b64 s[8:9], -1, 0
	v_writelane_b32 v254, s8, 6
	s_cmp_eq_u32 s11, 2
	s_nop 0
	v_writelane_b32 v254, s9, 7
	s_cselect_b64 s[8:9], -1, 0
	v_writelane_b32 v254, s8, 8
	s_cmp_eq_u32 s11, 1
	s_nop 0
	v_writelane_b32 v254, s9, 9
	s_cselect_b64 s[8:9], -1, 0
	v_writelane_b32 v254, s8, 10
	s_cmp_eq_u32 s11, 0
	s_nop 0
	v_writelane_b32 v254, s9, 11
	s_cselect_b64 s[8:9], -1, 0
	v_writelane_b32 v254, s8, 12
	s_nop 1
	v_writelane_b32 v254, s9, 13
	s_lshl_b32 s8, s10, 2
	s_add_u32 s4, s4, s8
	s_addc_u32 s5, s5, 0
	s_add_u32 s8, s4, 0x1400
	s_addc_u32 s9, s5, 0
	v_writelane_b32 v254, s8, 14
	s_add_u32 s4, s4, 0x2400
	s_addc_u32 s5, s5, 0
	v_writelane_b32 v254, s9, 15
	v_writelane_b32 v254, s4, 16
	s_nop 1
	v_writelane_b32 v254, s5, 17
	s_add_u32 s4, s0, 0x4400
	s_addc_u32 s5, s1, 0
	v_writelane_b32 v254, s4, 18
	s_add_u32 s0, s0, 0x4500
	s_addc_u32 s1, s1, 0
	v_writelane_b32 v254, s5, 19
	v_writelane_b32 v254, s0, 20
	s_cmpk_lt_i32 s84, 0x200
	s_nop 0
	v_writelane_b32 v254, s1, 21
	s_load_dword s1, s[62:63], 0xb0
	s_mul_i32 s0, s55, s54
	s_waitcnt lgkmcnt(0)
	s_mul_i32 s86, s0, s1
	s_cselect_b64 s[0:1], -1, 0
	v_writelane_b32 v254, s0, 22
	s_cmpk_lt_i32 s84, 0x100
	v_writelane_b32 v255, s86, 3
	v_writelane_b32 v254, s1, 23
	s_cselect_b64 s[0:1], -1, 0
	v_writelane_b32 v254, s0, 24
	s_cmpk_lt_i32 s2, 0x100
	s_nop 0
	v_writelane_b32 v254, s1, 25
	s_cselect_b64 s[0:1], -1, 0
	v_writelane_b32 v254, s0, 26
	s_nop 1
	v_writelane_b32 v254, s1, 27
	s_lshl_b32 s0, s7, 5
	s_cmpk_lt_i32 s2, 0x580
	s_cselect_b64 s[4:5], -1, 0
	s_cmp_lt_i32 s7, 0
	s_mul_i32 s1, s7, 33
	v_writelane_b32 v254, s4, 28
	s_cselect_b32 s0, s1, s0
	s_cselect_b32 s1, s87, 0x48
	v_writelane_b32 v254, s5, 29
	s_mul_i32 s1, s7, s1
	s_movk_i32 s4, 0xb1
	s_cselect_b32 s4, s4, 0xb0
	s_add_i32 s1, s1, s6
	s_mul_hi_i32 s5, s1, 0x38e38e39
	s_lshr_b32 s8, s5, 31
	s_ashr_i32 s5, s5, 3
	s_add_i32 s5, s5, s8
	s_mul_i32 s8, s5, 36
	s_sub_i32 s1, s1, s8
	s_bfe_i32 s8, s1, 0x80000
	s_bfe_u32 s8, s8, 0x2000d
	s_add_i32 s8, s1, s8
	s_and_b32 s9, s8, 0xfc
	s_add_i32 s0, s0, s6
	s_sub_i32 s1, s1, s9
	s_ashr_i32 s9, s0, 31
	s_lshr_b32 s9, s9, 28
	s_add_i32 s9, s0, s9
	s_and_b32 s10, s9, 0xfff0
	s_sub_i32 s0, s0, s10
	s_bfe_i32 s10, s0, 0x80000
	s_bfe_u32 s10, s10, 0x2000d
	s_add_i32 s10, s0, s10
	s_and_b32 s11, s10, 0xfc
	s_sub_i32 s11, s0, s11
	s_mul_i32 s0, s7, s4
	s_add_i32 s0, s0, s6
	s_mul_hi_i32 s4, s0, 0x2e8ba2e9
	s_lshr_b32 s6, s4, 31
	s_ashr_i32 s4, s4, 4
	s_add_i32 s4, s4, s6
	s_mul_i32 s6, s4, 0x58
	s_sub_i32 s0, s0, s6
	s_bfe_i32 s6, s0, 0x80000
	s_bfe_u32 s6, s6, 0x2000d
	s_add_i32 s6, s0, s6
	s_and_b32 s7, s6, 0xfc
	s_sub_i32 s7, s0, s7
	s_lshl_b32 s0, s5, 2
	s_bfe_i32 s5, s8, 0x80000
	s_sext_i32_i16 s5, s5
	s_sext_i32_i8 s1, s1
	s_add_i32 s12, s0, s1
	s_ashr_i32 s0, s5, 2
	v_writelane_b32 v254, s0, 30
	s_lshr_b32 s0, s5, 2
	s_bfe_i64 s[0:1], s[0:1], 0x100000
	s_lshl_b64 s[0:1], s[0:1], 19
	v_writelane_b32 v254, s0, 31
	s_sext_i32_i8 s5, s11
	s_ashr_i32 s13, s12, 31
	v_writelane_b32 v254, s1, 32
	s_ashr_i32 s0, s9, 4
	s_lshl_b32 s0, s0, 2
	s_bfe_i32 s1, s10, 0x80000
	s_sext_i32_i16 s1, s1
	s_add_i32 s8, s0, s5
	s_lshl_b32 s0, s4, 2
	s_sext_i32_i8 s5, s7
	s_bfe_i32 s4, s6, 0x80000
	s_add_i32 s6, s0, s5
	s_lshr_b32 s0, s1, 2
	s_ashr_i32 s93, s1, 2
	s_bfe_i64 s[0:1], s[0:1], 0x100000
	s_lshl_b64 s[0:1], s[0:1], 19
	s_sext_i32_i16 s4, s4
	v_writelane_b32 v254, s0, 33
	s_ashr_i32 s9, s8, 31
	s_ashr_i32 s7, s6, 31
	v_writelane_b32 v254, s1, 34
	s_ashr_i32 s0, s4, 2
	v_writelane_b32 v254, s0, 35
	s_lshr_b32 s0, s4, 2
	s_bfe_i64 s[0:1], s[0:1], 0x100000
	s_lshl_b64 s[0:1], s[0:1], 19
	v_writelane_b32 v254, s0, 36
	v_writelane_b32 v255, s93, 4
	s_nop 0
	v_writelane_b32 v254, s1, 37
	s_add_i32 s0, 0, 0x21000
	v_writelane_b32 v254, s0, 38
	s_add_i32 s0, 0, 0x21004
	v_writelane_b32 v254, s0, 39
	s_mov_b32 s0, s12
	v_writelane_b32 v254, s0, 40
	s_nop 1
	v_writelane_b32 v254, s1, 41
	s_lshl_b64 s[0:1], s[12:13], 19
	v_writelane_b32 v254, s0, 42
	s_nop 1
	v_writelane_b32 v254, s1, 43
	s_mov_b32 s0, s8
	v_writelane_b32 v254, s0, 44
	s_nop 1
	v_writelane_b32 v254, s1, 45
	s_lshl_b64 s[0:1], s[8:9], 19
	v_writelane_b32 v254, s0, 46
	s_nop 1
	v_writelane_b32 v254, s1, 47
	s_mov_b32 s0, s6
	v_writelane_b32 v254, s0, 48
	s_nop 1
	v_writelane_b32 v254, s1, 49
	s_lshl_b64 s[0:1], s[6:7], 19
	v_writelane_b32 v254, s0, 50
	s_nop 1
	v_writelane_b32 v254, s1, 51
	v_writelane_b32 v254, s64, 52
	s_nop 1
	v_writelane_b32 v254, s65, 53
	v_writelane_b32 v254, s66, 54
	s_nop 1
	v_writelane_b32 v254, s67, 55
	v_writelane_b32 v254, s68, 56
	s_nop 1
	v_writelane_b32 v254, s69, 57
	v_writelane_b32 v254, s70, 58
	s_nop 1
	v_writelane_b32 v254, s71, 59
	v_writelane_b32 v254, s74, 60
	s_nop 1
	v_writelane_b32 v254, s75, 61
	v_writelane_b32 v254, s76, 62
	s_nop 1
	v_writelane_b32 v254, s77, 63
	v_writelane_b32 v255, 0, 40
	v_writelane_b32 v255, 0, 41
	s_branch .LBB0_94

.LBB0_92:
	s_or_b64 exec, exec, s[0:1]
	v_readlane_b32 s12, v255, 40
	s_nop 1
	s_cmp_lg_u32 s12, 0
	s_cselect_b32 s13, 3, 0
	s_nop 0
	v_writelane_b32 v255, s13, 41
	s_mov_b64 s[0:1], 0
	s_waitcnt lgkmcnt(0)
	s_barrier

.LBB0_106:
	v_readlane_b32 s98, v255, 41
	s_nop 1
	s_cmp_eq_u32 s98, 0
	s_cbranch_scc1 .Lxw1_done
	s_mov_b32 m0, s98
	v_readlane_b32 s98, v254, 20
	v_readlane_b32 s99, v254, 21
	s_mov_b32 vcc_hi, 0
	s_nop 4
.Lxw1_poll:
	global_load_dword v130, v1, s[98:99] sc1
	s_waitcnt vmcnt(0)
	v_readfirstlane_b32 vcc_lo, v130
	s_nop 0
	s_cmp_ge_u32 vcc_lo, m0
	s_cbranch_scc1 .Lxw1_ok
	s_sleep 0
	s_add_i32 vcc_hi, vcc_hi, 1
	s_cmp_lt_u32 vcc_hi, 0x100000
	s_cbranch_scc1 .Lxw1_poll
.Lxw1_ok:
	v_writelane_b32 v255, 0, 41

.LBB0_505:
	s_andn2_saveexec_b64 s[4:5], s[4:5]
	s_cbranch_execz .LBB0_525
	s_mov_b64 s[4:5], exec
	v_readlane_b32 s12, v255, 40
	s_nop 1
	s_cmp_eq_u32 s12, 0
	s_cbranch_scc1 .Lxd2_glob
	buffer_wbl2 sc1
	s_waitcnt vmcnt(0)
	v_readlane_b32 s12, v254, 18
	v_readlane_b32 s13, v254, 19
	v_mov_b32_e32 v0, 1
	s_nop 4
	global_atomic_add v0, v1, v0, s[12:13] sc0
	s_waitcnt vmcnt(0)
	v_add_u32_e32 v0, 1, v0
	v_and_b32_e32 v0, 7, v0
	v_cmp_eq_u32_e32 vcc, 0, v0
	s_cbranch_vccz .Lxd2_nl
	v_readlane_b32 s12, v254, 20
	v_readlane_b32 s13, v254, 21
	v_mov_b32_e32 v0, 1
	s_nop 4
	global_atomic_add v1, v0, s[12:13]
.Lxd2_nl:
	v_readlane_b32 s12, v254, 16
	v_readlane_b32 s13, v254, 17
	v_mov_b32_e32 v0, 1
	s_nop 4
	global_atomic_add v1, v0, s[12:13]
	s_waitcnt vmcnt(0)
	s_branch .LBB0_525

.LBB0_525:
	s_or_b64 exec, exec, s[0:1]
	v_readlane_b32 s12, v255, 40
	s_lshl_b32 s13, s52, 1
	s_add_i32 s13, s13, 2
	s_cmp_lg_u32 s12, 0
	s_cselect_b32 s13, s13, 0
	s_nop 0
	v_writelane_b32 v255, s13, 41
	v_readlane_b32 s0, v254, 28
	s_mov_b64 s[4:5], s[62:63]
	v_mov_b32_e32 v10, v247
	v_readlane_b32 s1, v254, 29
	s_waitcnt lgkmcnt(0)
	s_barrier
	s_mul_i32 s22, s52, 0x2100
	s_mov_b32 s23, s59
	s_andn2_b64 vcc, exec, s[0:1]
	v_readfirstlane_b32 s6, v10
	s_cbranch_vccnz .LBB0_730
	v_lshlrev_b32_e32 v0, 4, v10
	v_add_u32_e32 v2, 0x2000, v0
	v_ashrrev_i32_e32 v3, 31, v2
	v_lshrrev_b32_e32 v3, 22, v3
	v_add_u32_e32 v3, v2, v3
	v_ashrrev_i32_e32 v11, 10, v3
	v_mul_i32_i24_e32 v3, 0x400, v11
	v_sub_u32_e32 v2, v2, v3
	v_lshrrev_b32_e32 v3, 4, v2
	v_bitop3_b32 v2, v3, v2, 32 bitop3:0x6c
	v_ashrrev_i32_e32 v3, 31, v2
	v_lshrrev_b32_e32 v3, 26, v3
	v_add_u32_e32 v3, v2, v3
	v_lshlrev_b32_e32 v4, 3, v11
	v_ashrrev_i32_e32 v12, 6, v3
	v_and_b32_e32 v4, -16, v4
	v_add_u32_e32 v4, v12, v4
	v_and_b32_e32 v5, 3, v12
	v_lshrrev_b32_e32 v6, 2, v4
	v_lshlrev_b32_e32 v7, 1, v4
	v_and_or_b32 v5, v4, s97, v5
	v_and_b32_e32 v6, 4, v6
	v_and_b32_e32 v7, 24, v7
	v_and_b32_e32 v3, 0xc0, v3
	v_or3_b32 v5, v5, v6, v7
	v_sub_u32_e32 v2, v2, v3
	v_mov_b32_e32 v7, 1
	v_lshlrev_b32_e32 v6, 5, v11
	v_ashrrev_i16_sdwa v2, v7, sext(v2) dst_sel:DWORD dst_unused:UNUSED_PAD src0_sel:DWORD src1_sel:BYTE_0
	v_and_b32_e32 v6, 32, v6
	v_bfe_i32 v13, v2, 0, 16
	v_add_lshl_u32 v2, v6, v13, 1
	v_lshl_add_u32 v156, v5, 11, v2
	v_lshl_add_u32 v158, v4, 11, v2
	v_bfe_i32 v2, v10, 27, 1
	v_lshrrev_b32_e32 v2, 22, v2
	v_add_u32_e32 v2, v0, v2
	s_load_dwordx2 s[0:1], s[4:5], 0xa0
	v_and_b32_e32 v2, 0xfffffc00, v2
	v_sub_u32_e32 v0, v0, v2
	v_lshrrev_b32_e32 v2, 4, v0
	v_ashrrev_i32_e32 v3, 31, v10
	v_bitop3_b32 v0, v2, v0, 32 bitop3:0x6c
	v_lshrrev_b32_e32 v3, 26, v3
	v_ashrrev_i32_e32 v2, 31, v0
	v_add_u32_e32 v3, v10, v3
	s_waitcnt lgkmcnt(0)
	s_add_u32 s70, s0, 0x3000000
	v_lshrrev_b32_e32 v2, 26, v2
	v_ashrrev_i32_e32 v15, 6, v3
	s_mov_b32 s93, s3
	s_addc_u32 s71, s1, 0
	s_mul_i32 s3, s52, 0x1700000
	v_add_u32_e32 v2, v0, v2
	v_lshlrev_b32_e32 v3, 3, v15
	s_load_dwordx4 s[44:47], s[4:5], 0x80
	s_add_u32 s4, s0, s3
	v_ashrrev_i32_e32 v14, 6, v2
	v_and_b32_e32 v3, -16, v3
	s_addc_u32 s5, s1, 0
	v_add_u32_e32 v3, v14, v3
	s_add_u32 s72, s4, 0x880000
	v_and_b32_e32 v4, 3, v14
	v_lshrrev_b32_e32 v5, 2, v3
	v_lshlrev_b32_e32 v6, 1, v3
	v_and_b32_e32 v2, 0xc0, v2
	s_addc_u32 s73, s5, 0
	s_ashr_i32 s5, s6, 6
	v_and_or_b32 v4, v3, s97, v4
	v_and_b32_e32 v5, 4, v5
	v_and_b32_e32 v6, 24, v6
	v_sub_u32_e32 v0, v0, v2
	s_ashr_i32 s4, s6, 8
	s_lshl_b32 s64, s5, 10
	v_or3_b32 v4, v4, v5, v6
	v_lshlrev_b32_e32 v5, 5, v15
	v_ashrrev_i16_sdwa v0, v7, sext(v0) dst_sel:DWORD dst_unused:UNUSED_PAD src0_sel:DWORD src1_sel:BYTE_0
	v_readlane_b32 s8, v254, 36
	v_and_b32_e32 v5, 32, v5
	v_bfe_i32 v16, v0, 0, 16
	v_readlane_b32 s9, v254, 37
	s_add_u32 s48, s72, s8
	v_add_lshl_u32 v2, v5, v16, 1
	s_addc_u32 s49, s73, s9
	s_add_i32 s65, s64, 0
	v_lshl_add_u32 v0, v4, 11, v2
	s_add_i32 m0, s65, 0x10000
	v_lshl_add_u32 v160, v3, 11, v2
	global_load_lds_dwordx4 v0, s[48:49]
	s_add_i32 m0, s65, 0x12000
	s_add_u32 s8, s48, 0x40000
	global_load_lds_dwordx4 v156, s[48:49]
	s_addc_u32 s9, s49, 0
	s_add_i32 m0, s65, 0x14000
	v_mov_b32_e32 v157, v1
	global_load_lds_dwordx4 v0, s[8:9]
	s_add_i32 m0, s65, 0x16000
	v_mov_b32_e32 v161, v1
	global_load_lds_dwordx4 v156, s[8:9]
	v_readlane_b32 s8, v254, 50
	v_readlane_b32 s9, v254, 51
	s_add_u32 s50, s70, s8
	s_addc_u32 s51, s71, s9
	s_add_i32 s66, s65, 0x2000
	s_mov_b32 m0, s65
	s_add_u32 s8, s50, 0x40000
	global_load_lds_dwordx4 v160, s[50:51]
	s_mov_b32 m0, s66
	s_addc_u32 s9, s51, 0
	s_add_i32 s67, s65, 0x4000
	global_load_lds_dwordx4 v158, s[50:51]
	s_mov_b32 m0, s67
	s_add_i32 s68, s65, 0x6000
	global_load_lds_dwordx4 v160, s[8:9]
	s_mov_b32 m0, s68
	s_cmp_eq_u32 s4, 1
	global_load_lds_dwordx4 v158, s[8:9]
	s_cselect_b64 s[8:9], -1, 0
	v_mov_b32_e32 v159, v1
	v_writelane_b32 v255, s8, 16
	v_lshl_add_u64 v[6:7], s[48:49], 0, v[0:1]
	v_lshl_add_u64 v[4:5], s[48:49], 0, v[156:157]
	v_lshl_add_u64 v[2:3], s[50:51], 0, v[160:161]
	v_writelane_b32 v255, s9, 17
	s_cmp_lg_u32 s4, 1
	v_lshl_add_u64 v[8:9], s[50:51], 0, v[158:159]
	s_cbranch_scc1 .LBB0_528
	s_barrier

.Lxw0_poll:
	global_load_dword v179, v1, s[98:99] sc1
	s_waitcnt vmcnt(0)
	v_readfirstlane_b32 vcc_lo, v179
	s_nop 0
	s_cmp_ge_u32 vcc_lo, m0
	s_cbranch_scc1 .Lxw0_ok
	s_sleep 0
	s_add_i32 vcc_hi, vcc_hi, 1
	s_cmp_lt_u32 vcc_hi, 0x100000
	s_cbranch_scc1 .Lxw0_poll
